# grid barrier: acquire-invalidate issued by wave 1 after the arrival barrier (waited before the closing barrier); thread 0 path has no invalidate
# speedup vs baseline: 1.0088x; 1.0088x over previous
; __device__ __forceinline__ unsigned xb_add(unsigned* p, unsigned v) { return __hip_atomic_fetch_add(p, v, __ATOMIC_RELAXED, __HIP_MEMORY_SCOPE_AGENT); }
; __device__ __forceinline__ void xcd_barrier(const XcdBarrier& b) {
;     asm volatile("s_waitcnt vmcnt(0)" ::: "memory");
;     __syncthreads();
;     if (threadIdx.x == 0) {
;         unsigned* bar = b.bar;
;         __builtin_amdgcn_s_waitcnt(0);
;         unsigned nloc = b.st[0], nx = b.st[1];
;         if (nloc == 0u) { xcd_barrier_complete(bar, b.x, nloc, nx); b.st[0] = nloc; b.st[1] = nx; }
;         const unsigned old = xb_add(&bar[XB_XSUB(b.x)], 1u);
.LBB0_1008:
	s_waitcnt vmcnt(0)
	s_waitcnt lgkmcnt(0)
	s_barrier
	v_readfirstlane_b32 s2, v191
	s_cmp_lg_u32 s2, 64
	s_cbranch_scc1 .Lxb_noinv
	buffer_inv sc1
.Lxb_noinv:
	s_mov_b64 s[0:1], exec
	v_readlane_b32 s2, v251, 2
	v_readlane_b32 s3, v251, 3
	s_and_b64 s[2:3], s[0:1], s[2:3]
	s_mov_b64 exec, s[2:3]
	s_cbranch_execz .LBB0_1061
	v_readlane_b32 s2, v254, 10
	s_waitcnt vmcnt(0) expcnt(0) lgkmcnt(0)
	s_nop 0
	v_mov_b32_e32 v0, s2
	ds_read_b32 v3, v0
	v_readlane_b32 s2, v254, 11
	s_waitcnt lgkmcnt(0)
	v_cmp_ne_u32_e32 vcc, 0, v3
	v_mov_b32_e32 v0, s2
	ds_read_b32 v2, v0
	s_cbranch_vccnz .LBB0_1025
	v_readlane_b32 s4, v251, 0
	v_readlane_b32 s5, v251, 1
	s_load_dwordx2 s[2:3], s[4:5], 0x4
	s_mov_b32 s9, 1
	s_waitcnt lgkmcnt(0)
	s_mul_i32 s8, s2, s92
	s_mul_i32 s8, s8, s3
	s_branch .LBB0_1013

; __device__ __forceinline__ void xcd_barrier(const XcdBarrier& b) {
;     ...
;         }
;     }
;     __syncthreads();
; }
.LBB0_1061:
	s_or_b64 exec, exec, s[0:1]
	s_mov_b64 s[0:1], 0
	s_waitcnt vmcnt(0) lgkmcnt(0)
	s_barrier
